# sample-attention wave task: loads de-serialised (Q rows, cached-K groups, new-K rows preloaded into a register queue, new-V rows)
# baseline (speedup 1.0000x reference)
; __device__ __forceinline__ void attn_sample_wave(float* wl  , const bf16_t* Q, const bf16_t* Kb, const bf16_t* Vb, const float* ck, const float* cv, bf16_t* MIX, const float* sinks, int task, int lane) {
;     const int g = task & 3, kvh = (task >> 2) & 1, b = task >> 3, head = kvh * 4 + g;
;     float* qs = wl; float* ps = wl + 256;
; #pragma unroll
;     for (int t = 0; t < 4; ++t) qs[t * 64 + lane] = bf2f(Q[(size_t)(MP + b * 4 + t) * 512 + head * 64 + lane]);
;     asm volatile("s_waitcnt lgkmcnt(0)" ::: "memory");
;     float sc[3][4];
; #pragma unroll
;     for (int slot = 0; slot < 3; ++slot) {
;         const int j = slot * 64 + lane; const bool have = (slot < 2) || (lane < 4);
;         float d0 = 0.f, d1 = 0.f, d2 = 0.f, d3 = 0.f;
;         if (have) {
;             if (slot < 2) { const float* kr = ck + ((size_t)b * 128 + j) * 128 + kvh * 64;
; #pragma unroll 8
;                 for (int d4 = 0; d4 < 16; ++d4) { const f32x4 kv = *(const f32x4*)(kr + 4 * d4);
; #pragma unroll
;                     for (int i = 0; i < 4; ++i) { const int d = 4 * d4 + i; d0 += kv[i] * qs[d]; d1 += kv[i] * qs[64 + d]; d2 += kv[i] * qs[128 + d]; d3 += kv[i] * qs[192 + d]; } }
.LBB0_1038:
	s_cmp_gt_i32 s20, -1
	s_mov_b64 s[0:1], -1
	s_cbranch_scc0 .LBB0_1057
	s_lshl_b32 s0, s20, 3
	v_readlane_b32 s1, v253, 62
	s_add_i32 s0, s0, s1
	s_waitcnt vmcnt(0)
	s_barrier
	ds_read2_b64 v[0:3], v101 offset0:4 offset1:5
	s_ashr_i32 s10, s0, 3
	s_lshl_b32 s11, s10, 2
	s_add_i32 s0, s11, 0x4000
	s_ashr_i32 s1, s0, 31
	s_lshl_b64 s[2:3], s[0:1], 10
	s_waitcnt lgkmcnt(0)
	v_readfirstlane_b32 s13, v1
	v_readfirstlane_b32 s12, v0
	v_lshl_add_u64 v[0:1], v[94:95], 0, s[2:3]
	global_load_ushort v208, v[0:1], off
	global_load_ushort v209, v[0:1], off offset:1024
	global_load_ushort v210, v[0:1], off offset:2048
	global_load_ushort v211, v[0:1], off offset:3072
	v_readfirstlane_b32 s8, v2
	v_readfirstlane_b32 s9, v3
	s_add_i32 s6, s11, 0x4001
	s_ashr_i32 s7, s6, 31
	s_lshl_b64 s[2:3], s[6:7], 10
	s_add_i32 s4, s11, 0x4002
	s_ashr_i32 s5, s4, 31
	s_lshl_b64 s[2:3], s[4:5], 10
	s_add_i32 s2, s11, 0x4003
	s_ashr_i32 s3, s2, 31
	s_lshl_b64 s[14:15], s[2:3], 10
	s_ashr_i32 s11, s10, 31
	s_lshl_b64 s[10:11], s[10:11], 16
	s_mov_b32 s14, 0
	s_waitcnt vmcnt(0)
	v_lshlrev_b32_e32 v2, 16, v208
	v_lshlrev_b32_e32 v0, 16, v209
	ds_write2st64_b32 v105, v2, v0 offset1:1
	v_lshlrev_b32_e32 v2, 16, v210
	v_lshlrev_b32_e32 v0, 16, v211
	ds_write2st64_b32 v105, v2, v0 offset0:2 offset1:3
	s_waitcnt lgkmcnt(0)
	v_lshl_add_u64 v[0:1], s[12:13], 0, v[108:109]
	v_mov_b32_e32 v2, 0
	v_lshl_add_u64 v[4:5], v[0:1], 0, s[10:11]
	v_mov_b32_e32 v3, v2
	v_mov_b32_e32 v0, v2
	v_mov_b32_e32 v1, v2
.LBB0_1040:
	global_load_dwordx4 v[8:11], v[4:5], off offset:-16
	global_load_dwordx4 v[12:15], v[4:5], off offset:-32
	global_load_dwordx4 v[16:19], v[4:5], off offset:-48
	global_load_dwordx4 v[20:23], v[4:5], off offset:-64
	global_load_dwordx4 v[208:211], v[4:5], off offset:48
	global_load_dwordx4 v[212:215], v[4:5], off offset:32
	global_load_dwordx4 v[216:219], v[4:5], off offset:16
	global_load_dwordx4 v[220:223], v[4:5], off
	s_add_i32 s15, s21, s14
	v_mov_b32_e32 v6, s15
	ds_read_b128 v[24:27], v6
	ds_read_b128 v[28:31], v6 offset:16
	ds_read_b128 v[32:35], v6 offset:32
	ds_read_b128 v[36:39], v6 offset:48
	ds_read_b128 v[40:43], v6 offset:256
	s_waitcnt lgkmcnt(4)
	v_mov_b32_e32 v44, v24
	v_mov_b32_e32 v24, v26
	s_addk_i32 s14, 0x80
	s_cmpk_lg_i32 s14, 0x100
	s_waitcnt lgkmcnt(0)
	v_mov_b32_e32 v45, v40
	v_mov_b32_e32 v40, v25
	v_mov_b32_e32 v25, v42
	v_mov_b32_e32 v42, v27
	s_waitcnt vmcnt(0)
	v_pk_fma_f32 v[2:3], v[20:21], v[44:45], v[2:3] op_sel_hi:[0,1,1]
	v_pk_fma_f32 v[2:3], v[20:21], v[40:41], v[2:3] op_sel:[1,0,0]
	v_mov_b32_e32 v44, v23
	v_pk_fma_f32 v[2:3], v[22:23], v[24:25], v[2:3] op_sel_hi:[0,1,1]
	v_pk_fma_f32 v[46:47], v[44:45], v[42:43], v[2:3] op_sel_hi:[0,1,1]
	ds_read_b128 v[24:27], v6 offset:512
	ds_read_b128 v[40:43], v6 offset:768
	s_waitcnt lgkmcnt(1)
	v_mov_b32_e32 v2, v24
	s_waitcnt lgkmcnt(0)
	v_mov_b32_e32 v3, v40
	v_pk_fma_f32 v[0:1], v[20:21], v[2:3], v[0:1] op_sel_hi:[0,1,1]
	v_mov_b32_e32 v40, v25
	v_pk_fma_f32 v[0:1], v[20:21], v[40:41], v[0:1] op_sel:[1,0,0]
	v_mov_b32_e32 v2, v26
	v_mov_b32_e32 v3, v42
	v_pk_fma_f32 v[0:1], v[22:23], v[2:3], v[0:1] op_sel_hi:[0,1,1]
	v_mov_b32_e32 v42, v27
	v_pk_fma_f32 v[24:25], v[44:45], v[42:43], v[0:1] op_sel_hi:[0,1,1]
	ds_read_b128 v[0:3], v6 offset:272
	v_mov_b32_e32 v20, v28
	v_mov_b32_e32 v26, v19
	s_waitcnt lgkmcnt(0)
	v_mov_b32_e32 v21, v0
	v_pk_fma_f32 v[20:21], v[16:17], v[20:21], v[46:47] op_sel_hi:[0,1,1]
	v_mov_b32_e32 v0, v29
	v_pk_fma_f32 v[0:1], v[16:17], v[0:1], v[20:21] op_sel:[1,0,0]
	v_mov_b32_e32 v20, v30
	v_mov_b32_e32 v21, v2
	v_pk_fma_f32 v[0:1], v[18:19], v[20:21], v[0:1] op_sel_hi:[0,1,1]
	v_mov_b32_e32 v2, v31
	v_pk_fma_f32 v[28:29], v[26:27], v[2:3], v[0:1] op_sel_hi:[0,1,1]
	ds_read_b128 v[0:3], v6 offset:528
	ds_read_b128 v[20:23], v6 offset:784
	s_waitcnt lgkmcnt(1)
	v_mov_b32_e32 v30, v0
	s_waitcnt lgkmcnt(0)
	v_mov_b32_e32 v31, v20
	v_pk_fma_f32 v[24:25], v[16:17], v[30:31], v[24:25] op_sel_hi:[0,1,1]
	v_mov_b32_e32 v20, v1
	v_pk_fma_f32 v[0:1], v[16:17], v[20:21], v[24:25] op_sel:[1,0,0]
	v_mov_b32_e32 v16, v2
	v_mov_b32_e32 v17, v22
	v_pk_fma_f32 v[0:1], v[18:19], v[16:17], v[0:1] op_sel_hi:[0,1,1]
	v_mov_b32_e32 v22, v3
	v_pk_fma_f32 v[20:21], v[26:27], v[22:23], v[0:1] op_sel_hi:[0,1,1]
	ds_read_b128 v[0:3], v6 offset:288
	v_mov_b32_e32 v16, v32
	v_mov_b32_e32 v22, v15
	s_waitcnt lgkmcnt(0)
	v_mov_b32_e32 v17, v0
	v_pk_fma_f32 v[16:17], v[12:13], v[16:17], v[28:29] op_sel_hi:[0,1,1]
	v_mov_b32_e32 v0, v33
	v_pk_fma_f32 v[0:1], v[12:13], v[0:1], v[16:17] op_sel:[1,0,0]
	v_mov_b32_e32 v16, v34
	v_mov_b32_e32 v17, v2
	v_pk_fma_f32 v[0:1], v[14:15], v[16:17], v[0:1] op_sel_hi:[0,1,1]
	v_mov_b32_e32 v2, v35
	v_pk_fma_f32 v[24:25], v[22:23], v[2:3], v[0:1] op_sel_hi:[0,1,1]
	ds_read_b128 v[0:3], v6 offset:544
	ds_read_b128 v[16:19], v6 offset:800
	s_waitcnt lgkmcnt(1)
	v_mov_b32_e32 v26, v0
	s_waitcnt lgkmcnt(0)
	v_mov_b32_e32 v27, v16
	v_pk_fma_f32 v[20:21], v[12:13], v[26:27], v[20:21] op_sel_hi:[0,1,1]
	v_mov_b32_e32 v16, v1
	v_pk_fma_f32 v[0:1], v[12:13], v[16:17], v[20:21] op_sel:[1,0,0]
	v_mov_b32_e32 v12, v2
	v_mov_b32_e32 v13, v18
	v_pk_fma_f32 v[0:1], v[14:15], v[12:13], v[0:1] op_sel_hi:[0,1,1]
	v_mov_b32_e32 v18, v3
	v_pk_fma_f32 v[20:21], v[22:23], v[18:19], v[0:1] op_sel_hi:[0,1,1]
	ds_read_b128 v[0:3], v6 offset:304
	v_mov_b32_e32 v12, v36
	v_mov_b32_e32 v22, v11
	s_waitcnt lgkmcnt(0)
	v_mov_b32_e32 v13, v0
	v_pk_fma_f32 v[12:13], v[8:9], v[12:13], v[24:25] op_sel_hi:[0,1,1]
	v_mov_b32_e32 v0, v37
	v_pk_fma_f32 v[0:1], v[8:9], v[0:1], v[12:13] op_sel:[1,0,0]
	v_mov_b32_e32 v12, v38
	v_mov_b32_e32 v13, v2
	v_pk_fma_f32 v[0:1], v[10:11], v[12:13], v[0:1] op_sel_hi:[0,1,1]
	ds_read_b128 v[12:15], v6 offset:560
	ds_read_b128 v[16:19], v6 offset:816
	v_mov_b32_e32 v2, v39
	v_pk_fma_f32 v[2:3], v[22:23], v[2:3], v[0:1] op_sel_hi:[0,1,1]
	s_waitcnt lgkmcnt(1)
; __device__ __forceinline__ void attn_sample_wave(float* wl  , const bf16_t* Q, const bf16_t* Kb, const bf16_t* Vb, const float* ck, const float* cv, bf16_t* MIX, const float* sinks, int task, int lane) {
;     ...
;             if (slot < 2) { const float* kr = ck + ((size_t)b * 128 + j) * 128 + kvh * 64;
; #pragma unroll 8
;                 for (int d4 = 0; d4 < 16; ++d4) { const f32x4 kv = *(const f32x4*)(kr + 4 * d4);
; #pragma unroll
;                     for (int i = 0; i < 4; ++i) { const int d = 4 * d4 + i; d0 += kv[i] * qs[d]; d1 += kv[i] * qs[64 + d]; d2 += kv[i] * qs[128 + d]; d3 += kv[i] * qs[192 + d]; } }
	v_mov_b32_e32 v0, v12
	s_waitcnt lgkmcnt(0)
	v_mov_b32_e32 v1, v16
	v_pk_fma_f32 v[0:1], v[8:9], v[0:1], v[20:21] op_sel_hi:[0,1,1]
	v_mov_b32_e32 v16, v13
	v_pk_fma_f32 v[0:1], v[8:9], v[16:17], v[0:1] op_sel:[1,0,0]
	v_mov_b32_e32 v8, v14
	v_mov_b32_e32 v9, v18
	v_pk_fma_f32 v[0:1], v[10:11], v[8:9], v[0:1] op_sel_hi:[0,1,1]
	v_mov_b32_e32 v18, v15
	v_pk_fma_f32 v[0:1], v[22:23], v[18:19], v[0:1] op_sel_hi:[0,1,1]
	ds_read_b128 v[24:27], v6 offset:64
	ds_read_b128 v[28:31], v6 offset:320
	v_lshl_add_u64 v[4:5], v[4:5], 0, s[82:83]
	s_waitcnt lgkmcnt(1)
	v_mov_b32_e32 v32, v24
	s_waitcnt lgkmcnt(0)
	v_mov_b32_e32 v33, v28
	v_mov_b32_e32 v28, v25
	v_mov_b32_e32 v24, v26
	v_mov_b32_e32 v25, v30
	v_mov_b32_e32 v30, v27
	v_pk_fma_f32 v[2:3], v[220:221], v[32:33], v[2:3] op_sel_hi:[0,1,1]
	v_pk_fma_f32 v[2:3], v[220:221], v[28:29], v[2:3] op_sel:[1,0,0]
	v_mov_b32_e32 v32, v223
	v_pk_fma_f32 v[2:3], v[222:223], v[24:25], v[2:3] op_sel_hi:[0,1,1]
	v_pk_fma_f32 v[34:35], v[32:33], v[30:31], v[2:3] op_sel_hi:[0,1,1]
	ds_read_b128 v[24:27], v6 offset:576
	ds_read_b128 v[28:31], v6 offset:832
	s_waitcnt lgkmcnt(1)
	v_mov_b32_e32 v2, v24
	s_waitcnt lgkmcnt(0)
	v_mov_b32_e32 v3, v28
	v_pk_fma_f32 v[0:1], v[220:221], v[2:3], v[0:1] op_sel_hi:[0,1,1]
	v_mov_b32_e32 v28, v25
	v_pk_fma_f32 v[0:1], v[220:221], v[28:29], v[0:1] op_sel:[1,0,0]
	v_mov_b32_e32 v2, v26
	v_mov_b32_e32 v3, v30
	v_pk_fma_f32 v[0:1], v[222:223], v[2:3], v[0:1] op_sel_hi:[0,1,1]
	v_mov_b32_e32 v30, v27
	v_pk_fma_f32 v[24:25], v[32:33], v[30:31], v[0:1] op_sel_hi:[0,1,1]
	ds_read_b128 v[0:3], v6 offset:80
	ds_read_b128 v[220:223], v6 offset:336
	s_waitcnt lgkmcnt(1)
	v_mov_b32_e32 v26, v0
	s_waitcnt lgkmcnt(0)
	v_mov_b32_e32 v27, v220
	v_pk_fma_f32 v[26:27], v[216:217], v[26:27], v[34:35] op_sel_hi:[0,1,1]
	v_mov_b32_e32 v220, v1
	v_pk_fma_f32 v[0:1], v[216:217], v[220:221], v[26:27] op_sel:[1,0,0]
	v_mov_b32_e32 v220, v2
	v_mov_b32_e32 v221, v222
	v_pk_fma_f32 v[0:1], v[218:219], v[220:221], v[0:1] op_sel_hi:[0,1,1]
	v_mov_b32_e32 v26, v219
	v_mov_b32_e32 v222, v3
	v_pk_fma_f32 v[28:29], v[26:27], v[222:223], v[0:1] op_sel_hi:[0,1,1]
	ds_read_b128 v[0:3], v6 offset:592
	ds_read_b128 v[220:223], v6 offset:848
	s_waitcnt lgkmcnt(1)
	v_mov_b32_e32 v30, v0
	s_waitcnt lgkmcnt(0)
	v_mov_b32_e32 v31, v220
	v_pk_fma_f32 v[24:25], v[216:217], v[30:31], v[24:25] op_sel_hi:[0,1,1]
	v_mov_b32_e32 v220, v1
	v_pk_fma_f32 v[0:1], v[216:217], v[220:221], v[24:25] op_sel:[1,0,0]
	v_mov_b32_e32 v216, v2
	v_mov_b32_e32 v217, v222
	v_pk_fma_f32 v[0:1], v[218:219], v[216:217], v[0:1] op_sel_hi:[0,1,1]
	v_mov_b32_e32 v222, v3
	v_pk_fma_f32 v[220:221], v[26:27], v[222:223], v[0:1] op_sel_hi:[0,1,1]
	ds_read_b128 v[0:3], v6 offset:96
	ds_read_b128 v[216:219], v6 offset:352
	s_waitcnt lgkmcnt(1)
	v_mov_b32_e32 v222, v0
	s_waitcnt lgkmcnt(0)
	v_mov_b32_e32 v223, v216
	v_pk_fma_f32 v[222:223], v[212:213], v[222:223], v[28:29] op_sel_hi:[0,1,1]
	v_mov_b32_e32 v216, v1
	v_pk_fma_f32 v[0:1], v[212:213], v[216:217], v[222:223] op_sel:[1,0,0]
	v_mov_b32_e32 v216, v2
	v_mov_b32_e32 v217, v218
	v_pk_fma_f32 v[0:1], v[214:215], v[216:217], v[0:1] op_sel_hi:[0,1,1]
	v_mov_b32_e32 v222, v215
	v_mov_b32_e32 v218, v3
	v_pk_fma_f32 v[24:25], v[222:223], v[218:219], v[0:1] op_sel_hi:[0,1,1]
	ds_read_b128 v[0:3], v6 offset:608
	ds_read_b128 v[216:219], v6 offset:864
	s_waitcnt lgkmcnt(1)
	v_mov_b32_e32 v26, v0
	s_waitcnt lgkmcnt(0)
	v_mov_b32_e32 v27, v216
	v_pk_fma_f32 v[220:221], v[212:213], v[26:27], v[220:221] op_sel_hi:[0,1,1]
	v_mov_b32_e32 v216, v1
	v_pk_fma_f32 v[0:1], v[212:213], v[216:217], v[220:221] op_sel:[1,0,0]
	v_mov_b32_e32 v212, v2
	v_mov_b32_e32 v213, v218
	v_pk_fma_f32 v[0:1], v[214:215], v[212:213], v[0:1] op_sel_hi:[0,1,1]
	v_mov_b32_e32 v218, v3
	v_pk_fma_f32 v[220:221], v[222:223], v[218:219], v[0:1] op_sel_hi:[0,1,1]
	ds_read_b128 v[0:3], v6 offset:112
	ds_read_b128 v[212:215], v6 offset:368
	v_mov_b32_e32 v222, v211
	s_waitcnt lgkmcnt(1)
	v_mov_b32_e32 v216, v0
	s_waitcnt lgkmcnt(0)
	v_mov_b32_e32 v217, v212
	v_pk_fma_f32 v[216:217], v[208:209], v[216:217], v[24:25] op_sel_hi:[0,1,1]
	v_mov_b32_e32 v212, v1
	v_pk_fma_f32 v[0:1], v[208:209], v[212:213], v[216:217] op_sel:[1,0,0]
	v_mov_b32_e32 v212, v2
	v_mov_b32_e32 v213, v214
	v_pk_fma_f32 v[0:1], v[210:211], v[212:213], v[0:1] op_sel_hi:[0,1,1]
	v_mov_b32_e32 v214, v3
	v_pk_fma_f32 v[2:3], v[222:223], v[214:215], v[0:1] op_sel_hi:[0,1,1]
	ds_read_b128 v[212:215], v6 offset:624
	ds_read_b128 v[216:219], v6 offset:880
	s_waitcnt lgkmcnt(1)
	v_mov_b32_e32 v0, v212
	s_waitcnt lgkmcnt(0)
	v_mov_b32_e32 v1, v216
	v_pk_fma_f32 v[0:1], v[208:209], v[0:1], v[220:221] op_sel_hi:[0,1,1]
	v_mov_b32_e32 v216, v213
	v_pk_fma_f32 v[0:1], v[208:209], v[216:217], v[0:1] op_sel:[1,0,0]
	v_mov_b32_e32 v6, v214
	v_mov_b32_e32 v7, v218
	v_pk_fma_f32 v[0:1], v[210:211], v[6:7], v[0:1] op_sel_hi:[0,1,1]
	v_mov_b32_e32 v218, v215
	v_pk_fma_f32 v[0:1], v[222:223], v[218:219], v[0:1] op_sel_hi:[0,1,1]
	s_cbranch_scc1 .LBB0_1040
	v_lshl_add_u64 v[4:5], s[12:13], 0, v[110:111]
	v_mov_b32_e32 v6, 0
	v_lshl_add_u64 v[8:9], v[4:5], 0, s[10:11]
	s_mov_b32 s12, 0
	v_mov_b32_e32 v7, v6
	v_mov_b32_e32 v4, v6
	v_mov_b32_e32 v5, v6
; __device__ __forceinline__ void attn_sample_wave(float* wl  , const bf16_t* Q, const bf16_t* Kb, const bf16_t* Vb, const float* ck, const float* cv, bf16_t* MIX, const float* sinks, int task, int lane) {
;     ...
;             if (slot < 2) { const float* kr = ck + ((size_t)b * 128 + j) * 128 + kvh * 64;
; #pragma unroll 8
;                 for (int d4 = 0; d4 < 16; ++d4) { const f32x4 kv = *(const f32x4*)(kr + 4 * d4);
; #pragma unroll
;                     for (int i = 0; i < 4; ++i) { const int d = 4 * d4 + i; d0 += kv[i] * qs[d]; d1 += kv[i] * qs[64 + d]; d2 += kv[i] * qs[128 + d]; d3 += kv[i] * qs[192 + d]; } }
.LBB0_1042:
	global_load_dwordx4 v[12:15], v[8:9], off offset:-16
	global_load_dwordx4 v[16:19], v[8:9], off offset:-32
	global_load_dwordx4 v[20:23], v[8:9], off offset:-48
	global_load_dwordx4 v[24:27], v[8:9], off offset:-64
	global_load_dwordx4 v[208:211], v[8:9], off offset:48
	global_load_dwordx4 v[212:215], v[8:9], off offset:32
	global_load_dwordx4 v[216:219], v[8:9], off offset:16
	global_load_dwordx4 v[220:223], v[8:9], off
	s_add_i32 s13, s21, s12
	v_mov_b32_e32 v10, s13
	ds_read_b128 v[28:31], v10
	ds_read_b128 v[32:35], v10 offset:16
	ds_read_b128 v[36:39], v10 offset:32
	ds_read_b128 v[40:43], v10 offset:48
	ds_read_b128 v[44:47], v10 offset:256
	s_waitcnt lgkmcnt(4)
	v_mov_b32_e32 v48, v28
	v_mov_b32_e32 v28, v30
	s_addk_i32 s12, 0x80
	s_cmpk_lg_i32 s12, 0x100
	s_waitcnt lgkmcnt(0)
	v_mov_b32_e32 v49, v44
	v_mov_b32_e32 v44, v29
	v_mov_b32_e32 v29, v46
	v_mov_b32_e32 v46, v31
	s_waitcnt vmcnt(0)
	v_pk_fma_f32 v[6:7], v[24:25], v[48:49], v[6:7] op_sel_hi:[0,1,1]
	v_pk_fma_f32 v[6:7], v[24:25], v[44:45], v[6:7] op_sel:[1,0,0]
	v_mov_b32_e32 v48, v27
	v_pk_fma_f32 v[6:7], v[26:27], v[28:29], v[6:7] op_sel_hi:[0,1,1]
	v_pk_fma_f32 v[50:51], v[48:49], v[46:47], v[6:7] op_sel_hi:[0,1,1]
	ds_read_b128 v[28:31], v10 offset:512
	ds_read_b128 v[44:47], v10 offset:768
	s_waitcnt lgkmcnt(1)
	v_mov_b32_e32 v6, v28
	s_waitcnt lgkmcnt(0)
	v_mov_b32_e32 v7, v44
	v_pk_fma_f32 v[4:5], v[24:25], v[6:7], v[4:5] op_sel_hi:[0,1,1]
	v_mov_b32_e32 v44, v29
	v_pk_fma_f32 v[4:5], v[24:25], v[44:45], v[4:5] op_sel:[1,0,0]
	v_mov_b32_e32 v6, v30
	v_mov_b32_e32 v7, v46
	v_pk_fma_f32 v[4:5], v[26:27], v[6:7], v[4:5] op_sel_hi:[0,1,1]
	v_mov_b32_e32 v46, v31
	v_pk_fma_f32 v[28:29], v[48:49], v[46:47], v[4:5] op_sel_hi:[0,1,1]
	ds_read_b128 v[4:7], v10 offset:272
	v_mov_b32_e32 v24, v32
	v_mov_b32_e32 v30, v23
	s_waitcnt lgkmcnt(0)
	v_mov_b32_e32 v25, v4
	v_pk_fma_f32 v[24:25], v[20:21], v[24:25], v[50:51] op_sel_hi:[0,1,1]
	v_mov_b32_e32 v4, v33
	v_pk_fma_f32 v[4:5], v[20:21], v[4:5], v[24:25] op_sel:[1,0,0]
	v_mov_b32_e32 v24, v34
	v_mov_b32_e32 v25, v6
	v_pk_fma_f32 v[4:5], v[22:23], v[24:25], v[4:5] op_sel_hi:[0,1,1]
	v_mov_b32_e32 v6, v35
	v_pk_fma_f32 v[32:33], v[30:31], v[6:7], v[4:5] op_sel_hi:[0,1,1]
	ds_read_b128 v[4:7], v10 offset:528
	ds_read_b128 v[24:27], v10 offset:784
	s_waitcnt lgkmcnt(1)
	v_mov_b32_e32 v34, v4
	s_waitcnt lgkmcnt(0)
	v_mov_b32_e32 v35, v24
	v_pk_fma_f32 v[28:29], v[20:21], v[34:35], v[28:29] op_sel_hi:[0,1,1]
	v_mov_b32_e32 v24, v5
	v_pk_fma_f32 v[4:5], v[20:21], v[24:25], v[28:29] op_sel:[1,0,0]
	v_mov_b32_e32 v20, v6
	v_mov_b32_e32 v21, v26
	v_pk_fma_f32 v[4:5], v[22:23], v[20:21], v[4:5] op_sel_hi:[0,1,1]
	v_mov_b32_e32 v26, v7
	v_pk_fma_f32 v[24:25], v[30:31], v[26:27], v[4:5] op_sel_hi:[0,1,1]
	ds_read_b128 v[4:7], v10 offset:288
	v_mov_b32_e32 v20, v36
	v_mov_b32_e32 v26, v19
	s_waitcnt lgkmcnt(0)
	v_mov_b32_e32 v21, v4
	v_pk_fma_f32 v[20:21], v[16:17], v[20:21], v[32:33] op_sel_hi:[0,1,1]
	v_mov_b32_e32 v4, v37
	v_pk_fma_f32 v[4:5], v[16:17], v[4:5], v[20:21] op_sel:[1,0,0]
	v_mov_b32_e32 v20, v38
	v_mov_b32_e32 v21, v6
	v_pk_fma_f32 v[4:5], v[18:19], v[20:21], v[4:5] op_sel_hi:[0,1,1]
	v_mov_b32_e32 v6, v39
	v_pk_fma_f32 v[28:29], v[26:27], v[6:7], v[4:5] op_sel_hi:[0,1,1]
	ds_read_b128 v[4:7], v10 offset:544
	ds_read_b128 v[20:23], v10 offset:800
	s_waitcnt lgkmcnt(1)
	v_mov_b32_e32 v30, v4
	s_waitcnt lgkmcnt(0)
	v_mov_b32_e32 v31, v20
	v_pk_fma_f32 v[24:25], v[16:17], v[30:31], v[24:25] op_sel_hi:[0,1,1]
	v_mov_b32_e32 v20, v5
	v_pk_fma_f32 v[4:5], v[16:17], v[20:21], v[24:25] op_sel:[1,0,0]
	v_mov_b32_e32 v16, v6
	v_mov_b32_e32 v17, v22
	v_pk_fma_f32 v[4:5], v[18:19], v[16:17], v[4:5] op_sel_hi:[0,1,1]
	v_mov_b32_e32 v22, v7
	v_pk_fma_f32 v[24:25], v[26:27], v[22:23], v[4:5] op_sel_hi:[0,1,1]
	ds_read_b128 v[4:7], v10 offset:304
	v_mov_b32_e32 v16, v40
	v_mov_b32_e32 v26, v15
	s_waitcnt lgkmcnt(0)
	v_mov_b32_e32 v17, v4
	v_pk_fma_f32 v[16:17], v[12:13], v[16:17], v[28:29] op_sel_hi:[0,1,1]
	v_mov_b32_e32 v4, v41
	v_pk_fma_f32 v[4:5], v[12:13], v[4:5], v[16:17] op_sel:[1,0,0]
	v_mov_b32_e32 v16, v42
	v_mov_b32_e32 v17, v6
	v_pk_fma_f32 v[4:5], v[14:15], v[16:17], v[4:5] op_sel_hi:[0,1,1]
	ds_read_b128 v[16:19], v10 offset:560
	ds_read_b128 v[20:23], v10 offset:816
	v_mov_b32_e32 v6, v43
	v_pk_fma_f32 v[6:7], v[26:27], v[6:7], v[4:5] op_sel_hi:[0,1,1]
	s_waitcnt lgkmcnt(1)
	v_mov_b32_e32 v4, v16
	s_waitcnt lgkmcnt(0)
	v_mov_b32_e32 v5, v20
	v_pk_fma_f32 v[4:5], v[12:13], v[4:5], v[24:25] op_sel_hi:[0,1,1]
	v_mov_b32_e32 v20, v17
	v_pk_fma_f32 v[4:5], v[12:13], v[20:21], v[4:5] op_sel:[1,0,0]
	v_mov_b32_e32 v12, v18
	v_mov_b32_e32 v13, v22
	v_pk_fma_f32 v[4:5], v[14:15], v[12:13], v[4:5] op_sel_hi:[0,1,1]
	v_mov_b32_e32 v22, v19
	v_pk_fma_f32 v[4:5], v[26:27], v[22:23], v[4:5] op_sel_hi:[0,1,1]
	ds_read_b128 v[28:31], v10 offset:64
	ds_read_b128 v[32:35], v10 offset:320
	v_lshl_add_u64 v[8:9], v[8:9], 0, s[82:83]
	s_waitcnt lgkmcnt(1)
	v_mov_b32_e32 v36, v28
	s_waitcnt lgkmcnt(0)
	v_mov_b32_e32 v37, v32
	v_mov_b32_e32 v32, v29
	v_mov_b32_e32 v28, v30
	v_mov_b32_e32 v29, v34
	v_mov_b32_e32 v34, v31
	v_pk_fma_f32 v[6:7], v[220:221], v[36:37], v[6:7] op_sel_hi:[0,1,1]
	v_pk_fma_f32 v[6:7], v[220:221], v[32:33], v[6:7] op_sel:[1,0,0]
	v_mov_b32_e32 v36, v223
	v_pk_fma_f32 v[6:7], v[222:223], v[28:29], v[6:7] op_sel_hi:[0,1,1]
	v_pk_fma_f32 v[38:39], v[36:37], v[34:35], v[6:7] op_sel_hi:[0,1,1]
	ds_read_b128 v[28:31], v10 offset:576
	ds_read_b128 v[32:35], v10 offset:832
	s_waitcnt lgkmcnt(1)
	v_mov_b32_e32 v6, v28
	s_waitcnt lgkmcnt(0)
; __device__ __forceinline__ void attn_sample_wave(float* wl  , const bf16_t* Q, const bf16_t* Kb, const bf16_t* Vb, const float* ck, const float* cv, bf16_t* MIX, const float* sinks, int task, int lane) {
;     ...
;             if (slot < 2) { const float* kr = ck + ((size_t)b * 128 + j) * 128 + kvh * 64;
; #pragma unroll 8
;                 for (int d4 = 0; d4 < 16; ++d4) { const f32x4 kv = *(const f32x4*)(kr + 4 * d4);
; #pragma unroll
;                     for (int i = 0; i < 4; ++i) { const int d = 4 * d4 + i; d0 += kv[i] * qs[d]; d1 += kv[i] * qs[64 + d]; d2 += kv[i] * qs[128 + d]; d3 += kv[i] * qs[192 + d]; } }
;             } else { const bf16_t* kr = Kb + (size_t)(MP + b * 4 + lane) * 128 + kvh * 64;
; #pragma unroll 16
;                 for (int d = 0; d < 64; ++d) { const float kv = bf2f(kr[d]); d0 += kv * qs[d]; d1 += kv * qs[64 + d]; d2 += kv * qs[128 + d]; d3 += kv * qs[192 + d]; } }
	v_mov_b32_e32 v7, v32
	v_pk_fma_f32 v[4:5], v[220:221], v[6:7], v[4:5] op_sel_hi:[0,1,1]
	v_mov_b32_e32 v32, v29
	v_pk_fma_f32 v[4:5], v[220:221], v[32:33], v[4:5] op_sel:[1,0,0]
	v_mov_b32_e32 v6, v30
	v_mov_b32_e32 v7, v34
	v_pk_fma_f32 v[4:5], v[222:223], v[6:7], v[4:5] op_sel_hi:[0,1,1]
	v_mov_b32_e32 v34, v31
	v_pk_fma_f32 v[28:29], v[36:37], v[34:35], v[4:5] op_sel_hi:[0,1,1]
	ds_read_b128 v[4:7], v10 offset:80
	ds_read_b128 v[220:223], v10 offset:336
	s_waitcnt lgkmcnt(1)
	v_mov_b32_e32 v30, v4
	s_waitcnt lgkmcnt(0)
	v_mov_b32_e32 v31, v220
	v_pk_fma_f32 v[30:31], v[216:217], v[30:31], v[38:39] op_sel_hi:[0,1,1]
	v_mov_b32_e32 v220, v5
	v_pk_fma_f32 v[4:5], v[216:217], v[220:221], v[30:31] op_sel:[1,0,0]
	v_mov_b32_e32 v220, v6
	v_mov_b32_e32 v221, v222
	v_pk_fma_f32 v[4:5], v[218:219], v[220:221], v[4:5] op_sel_hi:[0,1,1]
	v_mov_b32_e32 v30, v219
	v_mov_b32_e32 v222, v7
	v_pk_fma_f32 v[32:33], v[30:31], v[222:223], v[4:5] op_sel_hi:[0,1,1]
	ds_read_b128 v[4:7], v10 offset:592
	ds_read_b128 v[220:223], v10 offset:848
	s_waitcnt lgkmcnt(1)
	v_mov_b32_e32 v34, v4
	s_waitcnt lgkmcnt(0)
	v_mov_b32_e32 v35, v220
	v_pk_fma_f32 v[28:29], v[216:217], v[34:35], v[28:29] op_sel_hi:[0,1,1]
	v_mov_b32_e32 v220, v5
	v_pk_fma_f32 v[4:5], v[216:217], v[220:221], v[28:29] op_sel:[1,0,0]
	v_mov_b32_e32 v216, v6
	v_mov_b32_e32 v217, v222
	v_pk_fma_f32 v[4:5], v[218:219], v[216:217], v[4:5] op_sel_hi:[0,1,1]
	v_mov_b32_e32 v222, v7
	v_pk_fma_f32 v[220:221], v[30:31], v[222:223], v[4:5] op_sel_hi:[0,1,1]
	ds_read_b128 v[4:7], v10 offset:96
	ds_read_b128 v[216:219], v10 offset:352
	s_waitcnt lgkmcnt(1)
	v_mov_b32_e32 v222, v4
	s_waitcnt lgkmcnt(0)
	v_mov_b32_e32 v223, v216
	v_pk_fma_f32 v[222:223], v[212:213], v[222:223], v[32:33] op_sel_hi:[0,1,1]
	v_mov_b32_e32 v216, v5
	v_pk_fma_f32 v[4:5], v[212:213], v[216:217], v[222:223] op_sel:[1,0,0]
	v_mov_b32_e32 v216, v6
	v_mov_b32_e32 v217, v218
	v_pk_fma_f32 v[4:5], v[214:215], v[216:217], v[4:5] op_sel_hi:[0,1,1]
	v_mov_b32_e32 v222, v215
	v_mov_b32_e32 v218, v7
	v_pk_fma_f32 v[28:29], v[222:223], v[218:219], v[4:5] op_sel_hi:[0,1,1]
	ds_read_b128 v[4:7], v10 offset:608
	ds_read_b128 v[216:219], v10 offset:864
	s_waitcnt lgkmcnt(1)
	v_mov_b32_e32 v30, v4
	s_waitcnt lgkmcnt(0)
	v_mov_b32_e32 v31, v216
	v_pk_fma_f32 v[220:221], v[212:213], v[30:31], v[220:221] op_sel_hi:[0,1,1]
	v_mov_b32_e32 v216, v5
	v_pk_fma_f32 v[4:5], v[212:213], v[216:217], v[220:221] op_sel:[1,0,0]
	v_mov_b32_e32 v212, v6
	v_mov_b32_e32 v213, v218
	v_pk_fma_f32 v[4:5], v[214:215], v[212:213], v[4:5] op_sel_hi:[0,1,1]
	v_mov_b32_e32 v218, v7
	v_pk_fma_f32 v[220:221], v[222:223], v[218:219], v[4:5] op_sel_hi:[0,1,1]
	ds_read_b128 v[4:7], v10 offset:112
	ds_read_b128 v[212:215], v10 offset:368
	v_mov_b32_e32 v222, v211
	s_waitcnt lgkmcnt(1)
	v_mov_b32_e32 v216, v4
	s_waitcnt lgkmcnt(0)
	v_mov_b32_e32 v217, v212
	v_pk_fma_f32 v[216:217], v[208:209], v[216:217], v[28:29] op_sel_hi:[0,1,1]
	v_mov_b32_e32 v212, v5
	v_pk_fma_f32 v[4:5], v[208:209], v[212:213], v[216:217] op_sel:[1,0,0]
	v_mov_b32_e32 v212, v6
	v_mov_b32_e32 v213, v214
	v_pk_fma_f32 v[4:5], v[210:211], v[212:213], v[4:5] op_sel_hi:[0,1,1]
	v_mov_b32_e32 v214, v7
	v_pk_fma_f32 v[6:7], v[222:223], v[214:215], v[4:5] op_sel_hi:[0,1,1]
	ds_read_b128 v[212:215], v10 offset:624
	ds_read_b128 v[216:219], v10 offset:880
	s_waitcnt lgkmcnt(1)
	v_mov_b32_e32 v4, v212
	s_waitcnt lgkmcnt(0)
	v_mov_b32_e32 v5, v216
	v_pk_fma_f32 v[4:5], v[208:209], v[4:5], v[220:221] op_sel_hi:[0,1,1]
	v_mov_b32_e32 v216, v213
	v_pk_fma_f32 v[4:5], v[208:209], v[216:217], v[4:5] op_sel:[1,0,0]
	v_mov_b32_e32 v10, v214
	v_mov_b32_e32 v11, v218
	v_pk_fma_f32 v[4:5], v[210:211], v[10:11], v[4:5] op_sel_hi:[0,1,1]
	v_mov_b32_e32 v218, v215
	v_pk_fma_f32 v[4:5], v[222:223], v[218:219], v[4:5] op_sel_hi:[0,1,1]
	s_cbranch_scc1 .LBB0_1042
	v_mov_b32_e32 v11, 0
	v_mov_b32_e32 v9, 0xf149f2ca
	v_mov_b32_e32 v10, v11
	v_mov_b32_e32 v8, v11
	s_and_saveexec_b64 s[12:13], s[28:29]
	s_cbranch_execz .LBB0_1046
	v_add_u32_e32 v8, s0, v92
	v_ashrrev_i32_e32 v9, 31, v8
	v_readlane_b32 s14, v253, 43
	v_lshlrev_b64 v[8:9], 8, v[8:9]
	v_readlane_b32 s15, v253, 44
	s_mov_b32 s16, s21
	s_nop 0
	v_lshl_add_u64 v[12:13], s[14:15], 0, v[8:9]
	v_mov_b32_e32 v8, 0
	s_mov_b64 s[14:15], 0
	v_mov_b32_e32 v9, v8
	v_mov_b32_e32 v10, v8
	v_mov_b32_e32 v11, v8
	v_add_co_u32_e32 v46, vcc, 0x11300000, v12
	s_nop 1
	v_addc_co_u32_e32 v47, vcc, 0, v13, vcc
	global_load_dwordx4 v[208:211], v[46:47], off
	global_load_dwordx4 v[212:215], v[46:47], off offset:16
	global_load_dwordx4 v[216:219], v[46:47], off offset:32
	global_load_dwordx4 v[220:223], v[46:47], off offset:48
	global_load_dwordx4 v[224:227], v[46:47], off offset:64
	global_load_dwordx4 v[228:231], v[46:47], off offset:80
	global_load_dwordx4 v[232:235], v[46:47], off offset:96
	global_load_dwordx4 v[236:239], v[46:47], off offset:112
; __device__ __forceinline__ void attn_sample_wave(float* wl  , const bf16_t* Q, const bf16_t* Kb, const bf16_t* Vb, const float* ck, const float* cv, bf16_t* MIX, const float* sinks, int task, int lane) {
;     ...
;             } else { const bf16_t* kr = Kb + (size_t)(MP + b * 4 + lane) * 128 + kvh * 64;
; #pragma unroll 16
;                 for (int d = 0; d < 64; ++d) { const float kv = bf2f(kr[d]); d0 += kv * qs[d]; d1 += kv * qs[64 + d]; d2 += kv * qs[128 + d]; d3 += kv * qs[192 + d]; } }
.LBB0_1045:
	v_lshl_add_u64 v[14:15], v[12:13], 0, s[14:15]
	v_add_co_u32_e32 v46, vcc, 0x11300000, v14
	v_mov_b32_e32 v49, s16
	s_nop 0
	v_addc_co_u32_e32 v47, vcc, 0, v15, vcc
	s_waitcnt vmcnt(0)
	v_mov_b32_e32 v14, v208
	v_mov_b32_e32 v15, v209
	v_mov_b32_e32 v16, v210
	v_mov_b32_e32 v17, v211
	ds_read_b128 v[18:21], v49
	ds_read_b128 v[22:25], v49 offset:16
	ds_read_b128 v[26:29], v49 offset:32
	ds_read_b128 v[30:33], v49 offset:48
	ds_read_b128 v[34:37], v49 offset:256
	s_waitcnt lgkmcnt(4)
	v_mov_b32_e32 v39, v18
	s_add_u32 s14, s14, 32
	s_addc_u32 s15, s15, 0
	s_add_i32 s16, s16, 64
	s_waitcnt lgkmcnt(0)
	v_mov_b32_e32 v38, v34
	v_mov_b32_e32 v18, v35
	s_cmpk_lg_i32 s14, 0x80
	s_waitcnt vmcnt(0)
	v_lshlrev_b32_e32 v48, 16, v14
	v_pk_fma_f32 v[10:11], v[38:39], v[48:49], v[10:11] op_sel_hi:[1,0,1]
	ds_read_b128 v[38:41], v49 offset:512
	ds_read_b128 v[42:45], v49 offset:768
	v_and_b32_e32 v14, 0xffff0000, v14
	v_pk_fma_f32 v[10:11], v[18:19], v[14:15], v[10:11] op_sel_hi:[1,0,1]
	v_mov_b32_e32 v18, v36
	s_waitcnt lgkmcnt(1)
	v_mov_b32_e32 v50, v38
	s_waitcnt lgkmcnt(0)
	v_mov_b32_e32 v51, v42
	v_pk_fma_f32 v[8:9], v[50:51], v[48:49], v[8:9] op_sel_hi:[1,0,1]
	v_mov_b32_e32 v42, v39
	v_pk_fma_f32 v[8:9], v[42:43], v[14:15], v[8:9] op_sel_hi:[1,0,1]
	v_lshlrev_b32_e32 v14, 16, v15
	v_mov_b32_e32 v19, v20
	v_pk_fma_f32 v[10:11], v[18:19], v[14:15], v[10:11] op_sel_hi:[1,0,1]
	v_mov_b32_e32 v18, v40
	v_mov_b32_e32 v19, v44
	v_pk_fma_f32 v[8:9], v[18:19], v[14:15], v[8:9] op_sel_hi:[1,0,1]
	v_and_b32_e32 v14, 0xffff0000, v15
	v_mov_b32_e32 v20, v37
	v_mov_b32_e32 v44, v41
	v_pk_fma_f32 v[18:19], v[20:21], v[14:15], v[10:11] op_sel_hi:[1,0,1]
	v_pk_fma_f32 v[14:15], v[44:45], v[14:15], v[8:9] op_sel_hi:[1,0,1]
	ds_read_b128 v[8:11], v49 offset:272
	v_lshlrev_b32_e32 v38, 16, v16
	v_mov_b32_e32 v21, v22
	s_waitcnt lgkmcnt(0)
	v_mov_b32_e32 v20, v8
	v_pk_fma_f32 v[40:41], v[20:21], v[38:39], v[18:19] op_sel_hi:[1,0,1]
	ds_read_b128 v[18:21], v49 offset:528
	ds_read_b128 v[34:37], v49 offset:784
	v_and_b32_e32 v8, 0xffff0000, v16
	v_mov_b32_e32 v22, v9
	v_pk_fma_f32 v[22:23], v[22:23], v[8:9], v[40:41] op_sel_hi:[1,0,1]
	s_waitcnt lgkmcnt(1)
	v_mov_b32_e32 v42, v18
	s_waitcnt lgkmcnt(0)
	v_mov_b32_e32 v43, v34
	v_pk_fma_f32 v[14:15], v[42:43], v[38:39], v[14:15] op_sel_hi:[1,0,1]
	v_mov_b32_e32 v34, v19
	v_pk_fma_f32 v[8:9], v[34:35], v[8:9], v[14:15] op_sel_hi:[1,0,1]
	v_lshlrev_b32_e32 v14, 16, v17
	v_mov_b32_e32 v18, v10
	v_mov_b32_e32 v19, v24
	v_pk_fma_f32 v[18:19], v[18:19], v[14:15], v[22:23] op_sel_hi:[1,0,1]
	v_mov_b32_e32 v22, v20
	v_mov_b32_e32 v23, v36
	v_pk_fma_f32 v[8:9], v[22:23], v[14:15], v[8:9] op_sel_hi:[1,0,1]
	v_and_b32_e32 v10, 0xffff0000, v17
	v_mov_b32_e32 v24, v11
	v_mov_b32_e32 v36, v21
	v_pk_fma_f32 v[18:19], v[24:25], v[10:11], v[18:19] op_sel_hi:[1,0,1]
	v_pk_fma_f32 v[34:35], v[36:37], v[10:11], v[8:9] op_sel_hi:[1,0,1]
	v_mov_b32_e32 v8, v212
	v_mov_b32_e32 v9, v213
	v_mov_b32_e32 v10, v214
	v_mov_b32_e32 v11, v215
	ds_read_b128 v[14:17], v49 offset:288
	v_mov_b32_e32 v21, v26
	s_waitcnt lgkmcnt(0)
	v_mov_b32_e32 v20, v14
	v_mov_b32_e32 v26, v15
	s_waitcnt vmcnt(0)
	v_lshlrev_b32_e32 v36, 16, v8
	v_pk_fma_f32 v[38:39], v[20:21], v[36:37], v[18:19] op_sel_hi:[1,0,1]
	ds_read_b128 v[18:21], v49 offset:544
	ds_read_b128 v[22:25], v49 offset:800
	v_and_b32_e32 v8, 0xffff0000, v8
	v_pk_fma_f32 v[14:15], v[26:27], v[8:9], v[38:39] op_sel_hi:[1,0,1]
	v_lshlrev_b32_e32 v26, 16, v10
	s_waitcnt lgkmcnt(1)
	v_mov_b32_e32 v40, v18
	s_waitcnt lgkmcnt(0)
	v_mov_b32_e32 v41, v22
	v_pk_fma_f32 v[34:35], v[40:41], v[36:37], v[34:35] op_sel_hi:[1,0,1]
	v_mov_b32_e32 v22, v19
	v_pk_fma_f32 v[18:19], v[22:23], v[8:9], v[34:35] op_sel_hi:[1,0,1]
	v_lshlrev_b32_e32 v8, 16, v9
	v_mov_b32_e32 v22, v16
	v_mov_b32_e32 v23, v28
	v_pk_fma_f32 v[14:15], v[22:23], v[8:9], v[14:15] op_sel_hi:[1,0,1]
	v_mov_b32_e32 v22, v20
	v_mov_b32_e32 v23, v24
	v_pk_fma_f32 v[18:19], v[22:23], v[8:9], v[18:19] op_sel_hi:[1,0,1]
	v_and_b32_e32 v8, 0xffff0000, v9
	v_mov_b32_e32 v28, v17
	v_pk_fma_f32 v[22:23], v[28:29], v[8:9], v[14:15] op_sel_hi:[1,0,1]
	ds_read_b128 v[14:17], v49 offset:304
	v_mov_b32_e32 v24, v21
	v_pk_fma_f32 v[8:9], v[24:25], v[8:9], v[18:19] op_sel_hi:[1,0,1]
	v_mov_b32_e32 v19, v30
	v_and_b32_e32 v10, 0xffff0000, v10
	s_waitcnt lgkmcnt(0)
	v_mov_b32_e32 v18, v14
	v_pk_fma_f32 v[28:29], v[18:19], v[26:27], v[22:23] op_sel_hi:[1,0,1]
	ds_read_b128 v[18:21], v49 offset:560
	ds_read_b128 v[22:25], v49 offset:816
	v_mov_b32_e32 v30, v15
	v_pk_fma_f32 v[14:15], v[30:31], v[10:11], v[28:29] op_sel_hi:[1,0,1]
	s_waitcnt lgkmcnt(1)
	v_mov_b32_e32 v34, v18
	s_waitcnt lgkmcnt(0)
	v_mov_b32_e32 v35, v22
	v_pk_fma_f32 v[8:9], v[34:35], v[26:27], v[8:9] op_sel_hi:[1,0,1]
	v_mov_b32_e32 v22, v19
	v_pk_fma_f32 v[8:9], v[22:23], v[10:11], v[8:9] op_sel_hi:[1,0,1]
	v_lshlrev_b32_e32 v10, 16, v11
	v_mov_b32_e32 v18, v16
	v_mov_b32_e32 v19, v32
	v_pk_fma_f32 v[14:15], v[18:19], v[10:11], v[14:15] op_sel_hi:[1,0,1]
	v_mov_b32_e32 v18, v20
	v_mov_b32_e32 v19, v24
	v_pk_fma_f32 v[8:9], v[18:19], v[10:11], v[8:9] op_sel_hi:[1,0,1]
	v_and_b32_e32 v16, 0xffff0000, v11
	v_mov_b32_e32 v32, v17
	v_mov_b32_e32 v24, v21
	v_pk_fma_f32 v[10:11], v[32:33], v[16:17], v[14:15] op_sel_hi:[1,0,1]
	v_pk_fma_f32 v[8:9], v[24:25], v[16:17], v[8:9] op_sel_hi:[1,0,1]
	v_mov_b32_e32 v208, v216
	v_mov_b32_e32 v209, v217
	v_mov_b32_e32 v210, v218
	v_mov_b32_e32 v211, v219
	v_mov_b32_e32 v212, v220
	v_mov_b32_e32 v213, v221
	v_mov_b32_e32 v214, v222
	v_mov_b32_e32 v215, v223
	v_mov_b32_e32 v216, v224
	v_mov_b32_e32 v217, v225
	v_mov_b32_e32 v218, v226
	v_mov_b32_e32 v219, v227
	v_mov_b32_e32 v220, v228
	v_mov_b32_e32 v221, v229
	v_mov_b32_e32 v222, v230
	v_mov_b32_e32 v223, v231
	v_mov_b32_e32 v224, v232
	v_mov_b32_e32 v225, v233
	v_mov_b32_e32 v226, v234
	v_mov_b32_e32 v227, v235
	v_mov_b32_e32 v228, v236
	v_mov_b32_e32 v229, v237
	v_mov_b32_e32 v230, v238
	v_mov_b32_e32 v231, v239
	s_cbranch_scc1 .LBB0_1045

; __device__ __forceinline__ void attn_sample_wave(float* wl  , const bf16_t* Q, const bf16_t* Kb, const bf16_t* Vb, const float* ck, const float* cv, bf16_t* MIX, const float* sinks, int task, int lane) {
;     ...
;     for (int j0 = 0; j0 < 128; j0 += 32) { float vv[32];
; #pragma unroll
;         for (int jj = 0; jj < 32; ++jj) vv[jj] = vr[(size_t)(j0 + jj) * 128];
; #pragma unroll
;         for (int jj = 0; jj < 32; ++jj) { const int j = j0 + jj; const float v = vv[jj]; o0 += ps[j] * v; o1 += ps[132 + j] * v; o2 += ps[264 + j] * v; o3 += ps[396 + j] * v; } }
.LBB0_1055:
	global_load_dword v66, v[0:1], off
	global_load_dword v68, v[0:1], off offset:512
	global_load_dword v70, v[0:1], off offset:1024
	global_load_dword v72, v[0:1], off offset:1536
	global_load_dword v74, v[0:1], off offset:2048
	global_load_dword v76, v[0:1], off offset:2560
	global_load_dword v78, v[0:1], off offset:3072
	global_load_dword v80, v[0:1], off offset:3584
	v_add_co_u32_e32 v6, vcc, s81, v0
	s_add_i32 s10, s9, 0x44c
	s_nop 0
	v_addc_co_u32_e32 v7, vcc, 0, v1, vcc
	v_add_co_u32_e32 v20, vcc, s76, v0
	s_add_i32 s11, s9, 0x65c
	s_nop 0
	v_addc_co_u32_e32 v21, vcc, 0, v1, vcc
	global_load_dword v82, v[20:21], off offset:-4096
	global_load_dword v84, v[6:7], off offset:512
	global_load_dword v48, v[6:7], off offset:1024
	global_load_dword v46, v[6:7], off offset:1536
	global_load_dword v44, v[6:7], off offset:2048
	global_load_dword v38, v[6:7], off offset:2560
	global_load_dword v34, v[6:7], off offset:3072
	global_load_dword v26, v[6:7], off offset:3584
	global_load_dword v24, v[20:21], off
	global_load_dword v18, v[20:21], off offset:512
	global_load_dword v16, v[20:21], off offset:1024
	global_load_dword v14, v[20:21], off offset:1536
	global_load_dword v12, v[20:21], off offset:2048
	global_load_dword v10, v[20:21], off offset:2560
	global_load_dword v8, v[20:21], off offset:3072
	global_load_dword v6, v[20:21], off offset:3584
	v_add_co_u32_e32 v20, vcc, s89, v0
	v_mov_b32_e32 v7, s9
	s_nop 0
	v_addc_co_u32_e32 v21, vcc, 0, v1, vcc
	global_load_dword v42, v[20:21], off
	global_load_dword v40, v[20:21], off offset:512
	global_load_dword v36, v[20:21], off offset:1024
	global_load_dword v32, v[20:21], off offset:1536
	global_load_dword v30, v[20:21], off offset:2048
	global_load_dword v28, v[20:21], off offset:2560
	global_load_dword v22, v[20:21], off offset:3072
	s_nop 0
	global_load_dword v20, v[20:21], off offset:3584
	ds_read_b128 v[50:53], v7
	ds_read_b128 v[54:57], v7 offset:16
	ds_read_b96 v[62:64], v7 offset:32
	ds_read_b128 v[58:61], v7 offset:528
	v_mov_b32_e32 v9, s11
	s_waitcnt lgkmcnt(3)
	v_mov_b32_e32 v87, v50
	s_add_i32 s12, s9, 0x454
	s_add_i32 s13, s9, 0x664
	s_waitcnt lgkmcnt(0)
	v_mov_b32_e32 v86, v58
	v_mov_b32_e32 v50, v59
	v_mov_b32_e32 v59, v54
	s_add_i32 s14, s9, 0x45c
	s_add_i32 s15, s9, 0x66c
	s_add_i32 s16, s9, 0x464
	s_add_i32 s17, s9, 0x674
	s_add_i32 s18, s9, 0x46c
	s_add_i32 s19, s9, 0x67c
	s_addk_i32 s9, 0x80
	s_add_i32 s8, s8, 32
	v_lshl_add_u64 v[0:1], v[0:1], 0, s[90:91]
	s_cmpk_lt_u32 s8, 0x60
	s_waitcnt vmcnt(31)
	v_pk_fma_f32 v[4:5], v[66:67], v[86:87], v[4:5] op_sel_hi:[0,1,1]
	s_waitcnt vmcnt(30)
	v_pk_fma_f32 v[4:5], v[68:69], v[50:51], v[4:5] op_sel_hi:[0,1,1]
	v_mov_b32_e32 v50, v60
	v_mov_b32_e32 v51, v52
	s_waitcnt vmcnt(29)
	v_pk_fma_f32 v[4:5], v[70:71], v[50:51], v[4:5] op_sel_hi:[0,1,1]
	v_mov_b32_e32 v52, v61
	s_waitcnt vmcnt(28)
	v_pk_fma_f32 v[4:5], v[72:73], v[52:53], v[4:5] op_sel_hi:[0,1,1]
	ds_read_b128 v[50:53], v7 offset:544
	s_waitcnt lgkmcnt(0)
	v_mov_b32_e32 v58, v50
	s_waitcnt vmcnt(27)
	v_pk_fma_f32 v[4:5], v[74:75], v[58:59], v[4:5] op_sel_hi:[0,1,1]
	ds_read_b96 v[58:60], v7 offset:560
	v_mov_b32_e32 v54, v51
	s_waitcnt vmcnt(26)
	v_pk_fma_f32 v[4:5], v[76:77], v[54:55], v[4:5] op_sel_hi:[0,1,1]
	v_mov_b32_e32 v50, v52
	v_mov_b32_e32 v51, v56
	s_waitcnt vmcnt(25)
	v_pk_fma_f32 v[4:5], v[78:79], v[50:51], v[4:5] op_sel_hi:[0,1,1]
	v_mov_b32_e32 v56, v53
	s_waitcnt vmcnt(24)
	v_pk_fma_f32 v[4:5], v[80:81], v[56:57], v[4:5] op_sel_hi:[0,1,1]
	s_waitcnt lgkmcnt(0)
	v_mov_b32_e32 v50, v58
	v_mov_b32_e32 v51, v62
	v_mov_b32_e32 v62, v59
	ds_read_b128 v[52:55], v7 offset:1056
	ds_read_b128 v[56:59], v7 offset:1584
	s_waitcnt vmcnt(23)
	v_pk_fma_f32 v[4:5], v[82:83], v[50:51], v[4:5] op_sel_hi:[0,1,1]
	s_waitcnt vmcnt(22)
	v_pk_fma_f32 v[50:51], v[84:85], v[62:63], v[4:5] op_sel_hi:[0,1,1]
	s_waitcnt lgkmcnt(1)
	v_mov_b32_e32 v5, v52
	s_waitcnt lgkmcnt(0)
	v_mov_b32_e32 v4, v56
	v_pk_fma_f32 v[2:3], v[66:67], v[4:5], v[2:3] op_sel_hi:[0,1,1]
	v_mov_b32_e32 v52, v57
	v_pk_fma_f32 v[2:3], v[68:69], v[52:53], v[2:3] op_sel_hi:[0,1,1]
	v_mov_b32_e32 v4, v58
	v_mov_b32_e32 v5, v54
	v_pk_fma_f32 v[2:3], v[70:71], v[4:5], v[2:3] op_sel_hi:[0,1,1]
	v_mov_b32_e32 v54, v59
	v_pk_fma_f32 v[56:57], v[72:73], v[54:55], v[2:3] op_sel_hi:[0,1,1]
	ds_read_b128 v[2:5], v7 offset:1072
	ds_read_b128 v[52:55], v7 offset:1600
	s_waitcnt lgkmcnt(1)
	v_mov_b32_e32 v59, v2
	s_waitcnt lgkmcnt(0)
	v_mov_b32_e32 v58, v52
	v_pk_fma_f32 v[56:57], v[74:75], v[58:59], v[56:57] op_sel_hi:[0,1,1]
	v_mov_b32_e32 v2, v53
	v_pk_fma_f32 v[2:3], v[76:77], v[2:3], v[56:57] op_sel_hi:[0,1,1]
	v_mov_b32_e32 v52, v54
	v_mov_b32_e32 v53, v4
	v_pk_fma_f32 v[2:3], v[78:79], v[52:53], v[2:3] op_sel_hi:[0,1,1]
	v_mov_b32_e32 v4, v55
	v_pk_fma_f32 v[56:57], v[80:81], v[4:5], v[2:3] op_sel_hi:[0,1,1]
	ds_read_b96 v[52:54], v7 offset:1088
	ds_read_b96 v[2:4], v7 offset:1616
	s_waitcnt lgkmcnt(1)
	v_mov_b32_e32 v59, v52
	s_waitcnt lgkmcnt(0)
	v_mov_b32_e32 v58, v2
	v_pk_fma_f32 v[56:57], v[82:83], v[58:59], v[56:57] op_sel_hi:[0,1,1]
	v_mov_b32_e32 v52, v3
	v_pk_fma_f32 v[2:3], v[84:85], v[52:53], v[56:57] op_sel_hi:[0,1,1]
	v_mov_b32_e32 v52, v60
	v_mov_b32_e32 v53, v64
	v_mov_b32_e32 v5, v54
	s_waitcnt vmcnt(21)
	v_pk_fma_f32 v[50:51], v[48:49], v[52:53], v[50:51] op_sel_hi:[0,1,1]
	ds_read2_b32 v[52:53], v7 offset0:11 offset1:12
	ds_read2_b32 v[54:55], v7 offset0:143 offset1:144
	v_pk_fma_f32 v[2:3], v[48:49], v[4:5], v[2:3] op_sel_hi:[0,1,1]
	v_mov_b32_e32 v4, s10
	s_waitcnt lgkmcnt(1)
	v_mov_b32_e32 v57, v52
	s_waitcnt lgkmcnt(0)
	v_mov_b32_e32 v56, v54
	s_waitcnt vmcnt(20)
; __device__ __forceinline__ void attn_sample_wave(float* wl  , const bf16_t* Q, const bf16_t* Kb, const bf16_t* Vb, const float* ck, const float* cv, bf16_t* MIX, const float* sinks, int task, int lane) {
;     ...
;     for (int j0 = 0; j0 < 128; j0 += 32) { float vv[32];
; #pragma unroll
;         for (int jj = 0; jj < 32; ++jj) vv[jj] = vr[(size_t)(j0 + jj) * 128];
; #pragma unroll
;         for (int jj = 0; jj < 32; ++jj) { const int j = j0 + jj; const float v = vv[jj]; o0 += ps[j] * v; o1 += ps[132 + j] * v; o2 += ps[264 + j] * v; o3 += ps[396 + j] * v; } }
	v_pk_fma_f32 v[50:51], v[46:47], v[56:57], v[50:51] op_sel_hi:[0,1,1]
	v_mov_b32_e32 v52, v55
	s_waitcnt vmcnt(19)
	v_pk_fma_f32 v[50:51], v[44:45], v[52:53], v[50:51] op_sel_hi:[0,1,1]
	ds_read2_b32 v[52:53], v7 offset0:13 offset1:14
	ds_read2_b32 v[54:55], v7 offset0:145 offset1:146
	s_waitcnt lgkmcnt(1)
	v_mov_b32_e32 v57, v52
	s_waitcnt lgkmcnt(0)
	v_mov_b32_e32 v56, v54
	s_waitcnt vmcnt(18)
	v_pk_fma_f32 v[50:51], v[38:39], v[56:57], v[50:51] op_sel_hi:[0,1,1]
	v_mov_b32_e32 v52, v55
	s_waitcnt vmcnt(17)
	v_pk_fma_f32 v[50:51], v[34:35], v[52:53], v[50:51] op_sel_hi:[0,1,1]
	ds_read2_b32 v[52:53], v7 offset0:15 offset1:16
	ds_read2_b32 v[54:55], v7 offset0:147 offset1:148
	s_waitcnt lgkmcnt(1)
	v_mov_b32_e32 v57, v52
	s_waitcnt lgkmcnt(0)
	v_mov_b32_e32 v56, v54
	s_waitcnt vmcnt(16)
	v_pk_fma_f32 v[50:51], v[26:27], v[56:57], v[50:51] op_sel_hi:[0,1,1]
	v_mov_b32_e32 v52, v55
	s_waitcnt vmcnt(15)
	v_pk_fma_f32 v[50:51], v[24:25], v[52:53], v[50:51] op_sel_hi:[0,1,1]
	ds_read2_b32 v[52:53], v7 offset0:17 offset1:18
	ds_read2_b32 v[54:55], v7 offset0:149 offset1:150
	s_waitcnt lgkmcnt(1)
	v_mov_b32_e32 v57, v52
	s_waitcnt lgkmcnt(0)
	v_mov_b32_e32 v56, v54
	s_waitcnt vmcnt(14)
	v_pk_fma_f32 v[50:51], v[18:19], v[56:57], v[50:51] op_sel_hi:[0,1,1]
	v_mov_b32_e32 v52, v55
	s_waitcnt vmcnt(13)
	v_pk_fma_f32 v[50:51], v[16:17], v[52:53], v[50:51] op_sel_hi:[0,1,1]
	ds_read2_b32 v[52:53], v7 offset0:19 offset1:20
	ds_read2_b32 v[54:55], v7 offset0:151 offset1:152
	ds_read2_b32 v[4:5], v4 offset1:1
	ds_read2_b32 v[48:49], v9 offset1:1
	v_mov_b32_e32 v9, s13
	s_waitcnt lgkmcnt(3)
	v_mov_b32_e32 v57, v52
	s_waitcnt lgkmcnt(2)
	v_mov_b32_e32 v56, v54
	s_waitcnt vmcnt(12)
	v_pk_fma_f32 v[50:51], v[14:15], v[56:57], v[50:51] op_sel_hi:[0,1,1]
	v_mov_b32_e32 v52, v55
	s_waitcnt vmcnt(11)
	v_pk_fma_f32 v[50:51], v[12:13], v[52:53], v[50:51] op_sel_hi:[0,1,1]
	s_waitcnt lgkmcnt(0)
	v_mov_b32_e32 v52, v48
	v_mov_b32_e32 v53, v4
	v_pk_fma_f32 v[2:3], v[46:47], v[52:53], v[2:3] op_sel_hi:[0,1,1]
	v_mov_b32_e32 v4, v49
	v_pk_fma_f32 v[2:3], v[44:45], v[4:5], v[2:3] op_sel_hi:[0,1,1]
	v_mov_b32_e32 v4, s12
	ds_read2_b32 v[4:5], v4 offset1:1
	ds_read2_b32 v[44:45], v9 offset1:1
	v_mov_b32_e32 v9, s15
	s_waitcnt lgkmcnt(1)
	v_mov_b32_e32 v47, v4
	s_waitcnt lgkmcnt(0)
	v_mov_b32_e32 v46, v44
	v_pk_fma_f32 v[2:3], v[38:39], v[46:47], v[2:3] op_sel_hi:[0,1,1]
	v_mov_b32_e32 v4, v45
	v_pk_fma_f32 v[2:3], v[34:35], v[4:5], v[2:3] op_sel_hi:[0,1,1]
	v_mov_b32_e32 v4, s14
	ds_read2_b32 v[4:5], v4 offset1:1
	ds_read2_b32 v[34:35], v9 offset1:1
	v_mov_b32_e32 v9, s17
	s_waitcnt lgkmcnt(1)
	v_mov_b32_e32 v39, v4
	s_waitcnt lgkmcnt(0)
	v_mov_b32_e32 v38, v34
	v_pk_fma_f32 v[2:3], v[26:27], v[38:39], v[2:3] op_sel_hi:[0,1,1]
	v_mov_b32_e32 v4, v35
	v_pk_fma_f32 v[2:3], v[24:25], v[4:5], v[2:3] op_sel_hi:[0,1,1]
	v_mov_b32_e32 v4, s16
	ds_read2_b32 v[4:5], v4 offset1:1
	ds_read2_b32 v[24:25], v9 offset1:1
	v_mov_b32_e32 v9, s19
	s_waitcnt lgkmcnt(1)
	v_mov_b32_e32 v27, v4
	s_waitcnt lgkmcnt(0)
	v_mov_b32_e32 v26, v24
	v_pk_fma_f32 v[2:3], v[18:19], v[26:27], v[2:3] op_sel_hi:[0,1,1]
	v_mov_b32_e32 v4, v25
	v_pk_fma_f32 v[2:3], v[16:17], v[4:5], v[2:3] op_sel_hi:[0,1,1]
	v_mov_b32_e32 v4, s18
	ds_read2_b32 v[4:5], v4 offset1:1
	ds_read2_b32 v[16:17], v9 offset1:1
	s_waitcnt lgkmcnt(1)
	v_mov_b32_e32 v19, v4
	s_waitcnt lgkmcnt(0)
	v_mov_b32_e32 v18, v16
	v_pk_fma_f32 v[2:3], v[14:15], v[18:19], v[2:3] op_sel_hi:[0,1,1]
	v_mov_b32_e32 v4, v17
	v_pk_fma_f32 v[16:17], v[12:13], v[4:5], v[2:3] op_sel_hi:[0,1,1]
	ds_read_b32 v3, v7 offset:84
	ds_read_b32 v2, v7 offset:612
	ds_read_b32 v19, v7 offset:1140
	ds_read_b32 v18, v7 offset:1668
	s_waitcnt vmcnt(10) lgkmcnt(2)
	v_pk_fma_f32 v[24:25], v[10:11], v[2:3], v[50:51] op_sel_hi:[0,1,1]
	ds_read2_b64 v[2:5], v7 offset0:11 offset1:12
	ds_read2_b64 v[12:15], v7 offset0:77 offset1:78
	s_waitcnt lgkmcnt(1)
	v_mov_b32_e32 v27, v2
	s_waitcnt lgkmcnt(0)
	v_mov_b32_e32 v26, v12
	s_waitcnt vmcnt(9)
	v_pk_fma_f32 v[24:25], v[8:9], v[26:27], v[24:25] op_sel_hi:[0,1,1]
	v_mov_b32_e32 v2, v13
	s_waitcnt vmcnt(8)
	v_pk_fma_f32 v[2:3], v[6:7], v[2:3], v[24:25] op_sel_hi:[0,1,1]
	v_mov_b32_e32 v12, v14
	v_mov_b32_e32 v13, v4
	s_waitcnt vmcnt(7)
	v_pk_fma_f32 v[2:3], v[42:43], v[12:13], v[2:3] op_sel_hi:[0,1,1]
	v_mov_b32_e32 v4, v15
	s_waitcnt vmcnt(6)
	v_pk_fma_f32 v[24:25], v[40:41], v[4:5], v[2:3] op_sel_hi:[0,1,1]
	ds_read2_b64 v[2:5], v7 offset0:13 offset1:14
	ds_read2_b64 v[12:15], v7 offset0:79 offset1:80
	s_waitcnt lgkmcnt(1)
	v_mov_b32_e32 v27, v2
	s_waitcnt lgkmcnt(0)
	v_mov_b32_e32 v26, v12
	s_waitcnt vmcnt(5)
	v_pk_fma_f32 v[24:25], v[36:37], v[26:27], v[24:25] op_sel_hi:[0,1,1]
	v_mov_b32_e32 v2, v13
	s_waitcnt vmcnt(4)
	v_pk_fma_f32 v[2:3], v[32:33], v[2:3], v[24:25] op_sel_hi:[0,1,1]
	v_mov_b32_e32 v12, v14
	v_mov_b32_e32 v13, v4
	s_waitcnt vmcnt(3)
	v_pk_fma_f32 v[2:3], v[30:31], v[12:13], v[2:3] op_sel_hi:[0,1,1]
	v_mov_b32_e32 v4, v15
	s_waitcnt vmcnt(2)
	v_pk_fma_f32 v[2:3], v[28:29], v[4:5], v[2:3] op_sel_hi:[0,1,1]
	ds_read_b64 v[4:5], v7 offset:120
	ds_read_b64 v[12:13], v7 offset:648
	s_waitcnt lgkmcnt(1)
	v_mov_b32_e32 v15, v4
	s_waitcnt lgkmcnt(0)
	v_mov_b32_e32 v14, v12
	s_waitcnt vmcnt(1)
	v_pk_fma_f32 v[2:3], v[22:23], v[14:15], v[2:3] op_sel_hi:[0,1,1]
	v_mov_b32_e32 v4, v13
	s_waitcnt vmcnt(0)
	v_pk_fma_f32 v[4:5], v[20:21], v[4:5], v[2:3] op_sel_hi:[0,1,1]
	v_pk_fma_f32 v[2:3], v[10:11], v[18:19], v[16:17] op_sel_hi:[0,1,1]
	ds_read2_b64 v[10:13], v7 offset0:143 offset1:144
	ds_read2_b64 v[14:17], v7 offset0:209 offset1:210
	s_waitcnt lgkmcnt(1)
	v_mov_b32_e32 v19, v10
	s_waitcnt lgkmcnt(0)
	v_mov_b32_e32 v18, v14
	v_pk_fma_f32 v[2:3], v[8:9], v[18:19], v[2:3] op_sel_hi:[0,1,1]
	v_mov_b32_e32 v10, v15
	v_pk_fma_f32 v[2:3], v[6:7], v[10:11], v[2:3] op_sel_hi:[0,1,1]
	v_mov_b32_e32 v8, v16
	v_mov_b32_e32 v9, v12
	v_pk_fma_f32 v[2:3], v[42:43], v[8:9], v[2:3] op_sel_hi:[0,1,1]
	v_mov_b32_e32 v12, v17
	v_pk_fma_f32 v[2:3], v[40:41], v[12:13], v[2:3] op_sel_hi:[0,1,1]
	ds_read2_b64 v[8:11], v7 offset0:145 offset1:146
	ds_read2_b64 v[12:15], v7 offset0:211 offset1:212
	s_waitcnt lgkmcnt(1)
	v_mov_b32_e32 v17, v8
	s_waitcnt lgkmcnt(0)
	v_mov_b32_e32 v16, v12
	v_pk_fma_f32 v[2:3], v[36:37], v[16:17], v[2:3] op_sel_hi:[0,1,1]
	v_mov_b32_e32 v8, v13
	v_pk_fma_f32 v[2:3], v[32:33], v[8:9], v[2:3] op_sel_hi:[0,1,1]
	v_mov_b32_e32 v8, v14
	v_mov_b32_e32 v9, v10
	v_pk_fma_f32 v[2:3], v[30:31], v[8:9], v[2:3] op_sel_hi:[0,1,1]
	ds_read_b64 v[8:9], v7 offset:1176
	ds_read_b64 v[6:7], v7 offset:1704
	v_mov_b32_e32 v10, v15
	v_pk_fma_f32 v[2:3], v[28:29], v[10:11], v[2:3] op_sel_hi:[0,1,1]
	s_waitcnt lgkmcnt(1)
	v_mov_b32_e32 v11, v8
	s_waitcnt lgkmcnt(0)
	v_mov_b32_e32 v10, v6
	v_pk_fma_f32 v[2:3], v[22:23], v[10:11], v[2:3] op_sel_hi:[0,1,1]
	v_mov_b32_e32 v8, v7
	v_pk_fma_f32 v[2:3], v[20:21], v[8:9], v[2:3] op_sel_hi:[0,1,1]
	s_cbranch_scc1 .LBB0_1055
; __device__ __forceinline__ bf16_t f2bf(float f) { return (bf16_t)(cvt_pk_bf16(f, 0.f) & 0xffffu); }
; __device__ __forceinline__ void attn_sample_wave(float* wl  , const bf16_t* Q, const bf16_t* Kb, const bf16_t* Vb, const float* ck, const float* cv, bf16_t* MIX, const float* sinks, int task, int lane) {
;     ...
; #pragma unroll
;     for (int j = 0; j < 4; ++j) { const float v = bf2f(Vb[(size_t)(MP + b * 4 + j) * 128 + kvh * 64 + lane]); o0 += ps[128 + j] * v; o1 += ps[132 + 128 + j] * v; o2 += ps[264 + 128 + j] * v; o3 += ps[396 + 128 + j] * v; }
;     bf16_t* op = MIX + (size_t)(MP + b * 4) * 1024 + head * 64 + lane;
;     op[0] = f2bf(o0); op[1024] = f2bf(o1); op[2048] = f2bf(o2); op[3072] = f2bf(o3);
	s_lshl_b64 s[8:9], s[0:1], 8
	v_lshl_add_u64 v[0:1], v[96:97], 0, s[8:9]
	global_load_ushort v208, v[0:1], off
	s_lshl_b64 s[6:7], s[6:7], 8
	s_lshl_b64 s[4:5], s[4:5], 8
	s_lshl_b64 s[2:3], s[2:3], 8
	v_lshl_add_u64 v[210:211], v[96:97], 0, s[6:7]
	global_load_ushort v209, v[210:211], off
	v_lshl_add_u64 v[212:213], v[96:97], 0, s[4:5]
	global_load_ushort v214, v[212:213], off
	v_lshl_add_u64 v[216:217], v[96:97], 0, s[2:3]
	global_load_ushort v215, v[216:217], off
	v_mov_b32_e32 v1, s21
	ds_read_b128 v[6:9], v1 offset:1536
	ds_read_b128 v[10:13], v1 offset:2064
	ds_read_b128 v[14:17], v1 offset:2592
	ds_read_b128 v[18:21], v1 offset:3120
	s_lshl_b64 s[0:1], s[0:1], 11
	s_waitcnt vmcnt(0)
	v_lshlrev_b32_e32 v0, 16, v208
	s_waitcnt lgkmcnt(3)
	v_fma_f32 v5, v6, v0, v5
	s_waitcnt lgkmcnt(2)
	v_fmac_f32_e32 v4, v10, v0
	s_waitcnt lgkmcnt(1)
	v_fma_f32 v3, v14, v0, v3
	s_waitcnt lgkmcnt(0)
	v_fmac_f32_e32 v2, v18, v0
	v_lshlrev_b32_e32 v0, 16, v209
	v_fmac_f32_e32 v5, v7, v0
	v_fmac_f32_e32 v4, v11, v0
	v_fmac_f32_e32 v3, v15, v0
	v_fmac_f32_e32 v2, v19, v0
	v_lshlrev_b32_e32 v0, 16, v214
	v_fmac_f32_e32 v5, v8, v0
	v_fmac_f32_e32 v4, v12, v0
	v_fmac_f32_e32 v3, v16, v0
	v_fmac_f32_e32 v2, v20, v0
	v_lshlrev_b32_e32 v0, 16, v215
	v_fmac_f32_e32 v5, v9, v0
	v_fmac_f32_e32 v4, v13, v0
	v_fmac_f32_e32 v3, v17, v0
	v_fmac_f32_e32 v2, v21, v0
	v_lshl_add_u64 v[0:1], v[98:99], 0, s[0:1]
	v_cvt_pk_bf16_f32 v5, v5, s0
	v_cvt_pk_bf16_f32 v4, v4, s0
	global_store_short v[0:1], v5, off
	global_store_short v[0:1], v4, off offset:2048
	v_add_co_u32_e32 v0, vcc, 0x1000, v0
	v_cvt_pk_bf16_f32 v3, v3, s0
	s_nop 0
	v_addc_co_u32_e32 v1, vcc, 0, v1, vcc
	v_cvt_pk_bf16_f32 v2, v2, s0
	global_store_short v[0:1], v3, off
	global_store_short v[0:1], v2, off offset:2048
	s_waitcnt lgkmcnt(0)
	s_branch .LBB0_1037
